# weight-conversion loads (f32 weights, read once) marked nt
# speedup vs baseline: 1.0149x; 1.0070x over previous
.LBB0_34:
	s_ashr_i32 s72, s65, 9
	s_bfe_u32 s67, s65, 0x40005
	s_and_b32 s66, s25, 0x3e0
	s_mov_b64 s[2:3], -1
	s_mov_b64 s[36:37], 0
	s_cmp_lt_i32 s72, 4
	s_mov_b64 s[0:1], 0
	s_cbranch_scc1 .LBB0_145
	s_cmp_gt_i32 s72, 5
	s_cbranch_scc0 .LBB0_91
	s_cmp_gt_i32 s72, 6
	s_cbranch_scc0 .LBB0_64
	s_cmp_eq_u32 s72, 7
	s_mov_b64 s[0:1], -1
	s_cbranch_scc0 .LBB0_63
	s_lshl_b32 s26, s67, 6
	v_or_b32_e32 v64, s26, v12
	v_lshlrev_b32_e32 v0, 11, v64
	v_or3_b32 v0, v0, v13, s66
	v_lshlrev_b32_e32 v0, 2, v0
	v_lshl_add_u64 v[36:37], s[48:49], 0, v[0:1]
	v_add_co_u32_e32 v38, vcc, 0x1000, v36
	v_cmp_ne_u32_e64 s[2:3], 1, v35
	s_nop 0
	v_addc_co_u32_e32 v39, vcc, 0, v37, vcc
	v_add_co_u32_e32 v40, vcc, 0x5000, v36
	s_nop 1
	v_addc_co_u32_e32 v41, vcc, 0, v37, vcc
	v_add_co_u32_e32 v42, vcc, 0x9000, v36
	s_nop 1
	v_addc_co_u32_e32 v43, vcc, 0, v37, vcc
	v_add_co_u32_e32 v44, vcc, 0xd000, v36
	s_nop 1
	v_addc_co_u32_e32 v45, vcc, 0, v37, vcc
	v_add_co_u32_e32 v46, vcc, 0x11000, v36
	s_nop 1
	v_addc_co_u32_e32 v47, vcc, 0, v37, vcc
	v_add_co_u32_e32 v48, vcc, 0x15000, v36
	s_nop 1
	v_addc_co_u32_e32 v49, vcc, 0, v37, vcc
	v_add_co_u32_e32 v50, vcc, 0x19000, v36
	s_nop 1
	v_addc_co_u32_e32 v51, vcc, 0, v37, vcc
	v_add_co_u32_e32 v52, vcc, 0x1d000, v36
	s_nop 1
	v_addc_co_u32_e32 v53, vcc, 0, v37, vcc
	global_load_dword v68, v[38:39], off nt
	global_load_dword v67, v[40:41], off nt
	global_load_dword v66, v[42:43], off nt
	global_load_dword v65, v[44:45], off nt
	global_load_dword v58, v[46:47], off nt
	global_load_dword v62, v[48:49], off nt
	global_load_dword v59, v[50:51], off nt
	global_load_dword v57, v[52:53], off nt
	v_add_co_u32_e32 v38, vcc, 0x21000, v36
	s_nop 1
	v_addc_co_u32_e32 v39, vcc, 0, v37, vcc
	v_add_co_u32_e32 v40, vcc, 0x25000, v36
	s_nop 1
	v_addc_co_u32_e32 v41, vcc, 0, v37, vcc
	v_add_co_u32_e32 v42, vcc, 0x29000, v36
	s_nop 1
	v_addc_co_u32_e32 v43, vcc, 0, v37, vcc
	v_add_co_u32_e32 v44, vcc, 0x2d000, v36
	s_nop 1
	v_addc_co_u32_e32 v45, vcc, 0, v37, vcc
	v_add_co_u32_e32 v46, vcc, 0x31000, v36
	s_nop 1
	v_addc_co_u32_e32 v47, vcc, 0, v37, vcc
	v_add_co_u32_e32 v48, vcc, 0x35000, v36
	s_nop 1
	v_addc_co_u32_e32 v49, vcc, 0, v37, vcc
	v_add_co_u32_e32 v52, vcc, 0x39000, v36
	s_nop 1
	v_addc_co_u32_e32 v53, vcc, 0, v37, vcc
	v_add_co_u32_e32 v70, vcc, 0x3d000, v36
	s_nop 1
	v_addc_co_u32_e32 v71, vcc, 0, v37, vcc
	global_load_dword v60, v[38:39], off nt
	global_load_dword v63, v[40:41], off nt
	global_load_dword v61, v[42:43], off nt
	global_load_dword v56, v[44:45], off nt
	global_load_dword v50, v[46:47], off nt
	global_load_dword v54, v[48:49], off nt
	global_load_dword v51, v[52:53], off nt
	s_nop 0
	global_load_dword v49, v[70:71], off nt
	v_add_co_u32_e32 v38, vcc, 0x41000, v36
	s_nop 1
	v_addc_co_u32_e32 v39, vcc, 0, v37, vcc
	v_add_co_u32_e32 v40, vcc, 0x45000, v36
	s_nop 1
	v_addc_co_u32_e32 v41, vcc, 0, v37, vcc
	v_add_co_u32_e32 v42, vcc, 0x49000, v36
	s_nop 1
	v_addc_co_u32_e32 v43, vcc, 0, v37, vcc
	v_add_co_u32_e32 v44, vcc, 0x4d000, v36
	s_nop 1
	v_addc_co_u32_e32 v45, vcc, 0, v37, vcc
	v_add_co_u32_e32 v46, vcc, 0x51000, v36
	s_nop 1
	v_addc_co_u32_e32 v47, vcc, 0, v37, vcc
	v_add_co_u32_e32 v70, vcc, 0x55000, v36
	s_nop 1
	v_addc_co_u32_e32 v71, vcc, 0, v37, vcc
	v_add_co_u32_e32 v72, vcc, 0x59000, v36
	s_nop 1
	v_addc_co_u32_e32 v73, vcc, 0, v37, vcc
	v_add_co_u32_e32 v74, vcc, 0x5d000, v36
	s_nop 1
	v_addc_co_u32_e32 v75, vcc, 0, v37, vcc
	global_load_dword v52, v[38:39], off nt
	global_load_dword v55, v[40:41], off nt
	global_load_dword v53, v[42:43], off nt
	global_load_dword v48, v[44:45], off nt
	s_nop 0
	global_load_dword v42, v[46:47], off nt
	s_nop 0
	global_load_dword v46, v[70:71], off nt
	global_load_dword v43, v[72:73], off nt
	global_load_dword v41, v[74:75], off nt
	v_add_co_u32_e32 v38, vcc, 0x61000, v36
	s_nop 1
	v_addc_co_u32_e32 v39, vcc, 0, v37, vcc
	v_add_co_u32_e32 v70, vcc, 0x65000, v36
	s_nop 1
	v_addc_co_u32_e32 v71, vcc, 0, v37, vcc
	v_add_co_u32_e32 v72, vcc, 0x69000, v36
	s_nop 1
	v_addc_co_u32_e32 v73, vcc, 0, v37, vcc
	v_add_co_u32_e32 v74, vcc, 0x6d000, v36
	s_nop 1
	v_addc_co_u32_e32 v75, vcc, 0, v37, vcc
	v_add_co_u32_e32 v76, vcc, 0x71000, v36
	s_nop 1
	v_addc_co_u32_e32 v77, vcc, 0, v37, vcc
	v_add_co_u32_e32 v78, vcc, 0x75000, v36
	s_nop 1
	v_addc_co_u32_e32 v79, vcc, 0, v37, vcc
	v_add_co_u32_e32 v80, vcc, 0x79000, v36
	s_nop 1
	v_addc_co_u32_e32 v81, vcc, 0, v37, vcc
	v_add_co_u32_e32 v82, vcc, 0x7d000, v36
	s_nop 1
	v_addc_co_u32_e32 v83, vcc, 0, v37, vcc
	global_load_dword v44, v[38:39], off nt
	global_load_dword v47, v[70:71], off nt
	global_load_dword v45, v[72:73], off nt
	global_load_dword v40, v[74:75], off nt
	global_load_dword v36, v[76:77], off nt
	s_nop 0
	global_load_dword v38, v[78:79], off nt
	global_load_dword v37, v[80:81], off nt
	global_load_dword v0, v[82:83], off nt
	s_andn2_b64 vcc, exec, s[28:29]
	v_add_lshl_u32 v39, s26, v12, 2
	s_cbranch_vccnz .LBB0_280
	v_lshlrev_b32_e32 v64, 2, v64
	global_load_dword v69, v64, s[46:47]
	global_load_dword v70, v39, s[46:47] offset:8
	global_load_dword v71, v39, s[46:47] offset:16
	s_nop 0
	global_load_dword v64, v39, s[46:47] offset:24
	v_add_u32_e32 v72, v14, v16
	s_waitcnt vmcnt(3)
	v_mul_f32_e32 v73, v68, v69
	s_waitcnt vmcnt(2)
	v_mul_f32_e32 v70, v67, v70
	s_waitcnt vmcnt(1)
	v_mul_f32_e32 v69, v66, v71
	ds_write_b32 v15, v73
	ds_write_b32 v72, v70
	s_cbranch_execnz .LBB0_41

.LBB0_64:
	s_and_b64 vcc, exec, s[2:3]
	s_cbranch_vccz .LBB0_90
	s_lshl_b32 s26, s67, 6
	v_or_b32_e32 v64, s26, v12
	v_lshlrev_b32_e32 v0, 11, v64
	v_or3_b32 v0, v0, v13, s66
	v_lshlrev_b32_e32 v0, 2, v0
	v_lshl_add_u64 v[36:37], s[48:49], 0, v[0:1]
	v_add_co_u32_e32 v38, vcc, 0x4000, v36
	v_cmp_ne_u32_e64 s[2:3], 1, v35
	s_nop 0
	v_addc_co_u32_e32 v39, vcc, 0, v37, vcc
	v_add_co_u32_e32 v40, vcc, 0x8000, v36
	s_nop 1
	v_addc_co_u32_e32 v41, vcc, 0, v37, vcc
	v_add_co_u32_e32 v42, vcc, 0xc000, v36
	s_nop 1
	v_addc_co_u32_e32 v43, vcc, 0, v37, vcc
	v_add_co_u32_e32 v44, vcc, 0x10000, v36
	s_nop 1
	v_addc_co_u32_e32 v45, vcc, 0, v37, vcc
	v_add_co_u32_e32 v46, vcc, 0x14000, v36
	s_nop 1
	v_addc_co_u32_e32 v47, vcc, 0, v37, vcc
	v_add_co_u32_e32 v48, vcc, 0x18000, v36
	s_nop 1
	v_addc_co_u32_e32 v49, vcc, 0, v37, vcc
	v_add_co_u32_e32 v50, vcc, 0x1c000, v36
	s_nop 1
	v_addc_co_u32_e32 v51, vcc, 0, v37, vcc
	v_add_co_u32_e32 v52, vcc, 0x20000, v36
	s_nop 1
	v_addc_co_u32_e32 v53, vcc, 0, v37, vcc
	global_load_dword v67, v[38:39], off nt
	global_load_dword v66, v[40:41], off nt
	global_load_dword v65, v[42:43], off nt
	global_load_dword v59, v[44:45], off nt
	global_load_dword v62, v[46:47], off nt
	global_load_dword v60, v[48:49], off nt
	global_load_dword v57, v[50:51], off nt
	global_load_dword v56, v[52:53], off nt
	v_add_co_u32_e32 v38, vcc, 0x24000, v36
	s_nop 1
	v_addc_co_u32_e32 v39, vcc, 0, v37, vcc
	v_add_co_u32_e32 v40, vcc, 0x28000, v36
	s_nop 1
	v_addc_co_u32_e32 v41, vcc, 0, v37, vcc
	v_add_co_u32_e32 v42, vcc, 0x2c000, v36
	s_nop 1
	v_addc_co_u32_e32 v43, vcc, 0, v37, vcc
	v_add_co_u32_e32 v44, vcc, 0x30000, v36
	s_nop 1
	v_addc_co_u32_e32 v45, vcc, 0, v37, vcc
	v_add_co_u32_e32 v46, vcc, 0x34000, v36
	s_nop 1
	v_addc_co_u32_e32 v47, vcc, 0, v37, vcc
	v_add_co_u32_e32 v48, vcc, 0x38000, v36
	s_nop 1
	v_addc_co_u32_e32 v49, vcc, 0, v37, vcc
	v_add_co_u32_e32 v68, vcc, 0x3c000, v36
	s_nop 1
	v_addc_co_u32_e32 v69, vcc, 0, v37, vcc
	v_add_co_u32_e32 v70, vcc, 0x40000, v36
	s_nop 1
	v_addc_co_u32_e32 v71, vcc, 0, v37, vcc
	global_load_dword v63, v[38:39], off nt
	global_load_dword v61, v[40:41], off nt
	global_load_dword v58, v[42:43], off nt
	global_load_dword v51, v[44:45], off nt
	global_load_dword v54, v[46:47], off nt
	global_load_dword v52, v[48:49], off nt
	s_nop 0
	global_load_dword v49, v[68:69], off nt
	global_load_dword v48, v[70:71], off nt
	v_add_co_u32_e32 v38, vcc, 0x44000, v36
	s_nop 1
	v_addc_co_u32_e32 v39, vcc, 0, v37, vcc
	v_add_co_u32_e32 v40, vcc, 0x48000, v36
	s_nop 1
	v_addc_co_u32_e32 v41, vcc, 0, v37, vcc
	v_add_co_u32_e32 v42, vcc, 0x4c000, v36
	s_nop 1
	v_addc_co_u32_e32 v43, vcc, 0, v37, vcc
	v_add_co_u32_e32 v44, vcc, 0x50000, v36
	s_nop 1
	v_addc_co_u32_e32 v45, vcc, 0, v37, vcc
	v_add_co_u32_e32 v46, vcc, 0x54000, v36
	s_nop 1
	v_addc_co_u32_e32 v47, vcc, 0, v37, vcc
	v_add_co_u32_e32 v68, vcc, 0x58000, v36
	s_nop 1
	v_addc_co_u32_e32 v69, vcc, 0, v37, vcc
	v_add_co_u32_e32 v70, vcc, 0x5c000, v36
	s_nop 1
	v_addc_co_u32_e32 v71, vcc, 0, v37, vcc
	v_add_co_u32_e32 v72, vcc, 0x60000, v36
	s_nop 1
	v_addc_co_u32_e32 v73, vcc, 0, v37, vcc
	global_load_dword v55, v[38:39], off nt
	global_load_dword v53, v[40:41], off nt
	global_load_dword v50, v[42:43], off nt
	s_nop 0
	global_load_dword v45, v[44:45], off nt
	s_nop 0
	global_load_dword v47, v[46:47], off nt
	s_nop 0
	global_load_dword v46, v[68:69], off nt
	global_load_dword v42, v[70:71], off nt
	global_load_dword v39, v[72:73], off nt
	v_add_co_u32_e32 v40, vcc, 0x64000, v36
	s_nop 1
	v_addc_co_u32_e32 v41, vcc, 0, v37, vcc
	v_add_co_u32_e32 v70, vcc, 0x68000, v36
	s_nop 1
	v_addc_co_u32_e32 v71, vcc, 0, v37, vcc
	v_add_co_u32_e32 v72, vcc, 0x6c000, v36
	s_nop 1
	v_addc_co_u32_e32 v73, vcc, 0, v37, vcc
	v_add_co_u32_e32 v74, vcc, 0x70000, v36
	s_nop 1
	v_addc_co_u32_e32 v75, vcc, 0, v37, vcc
	v_add_co_u32_e32 v76, vcc, 0x74000, v36
	s_nop 1
	v_addc_co_u32_e32 v77, vcc, 0, v37, vcc
	v_add_co_u32_e32 v78, vcc, 0x78000, v36
	s_nop 1
	v_addc_co_u32_e32 v79, vcc, 0, v37, vcc
	v_add_co_u32_e32 v80, vcc, 0x7c000, v36
	s_nop 1
	v_addc_co_u32_e32 v81, vcc, 0, v37, vcc
	global_load_dword v68, v0, s[48:49]
	global_load_dword v44, v[40:41], off nt
	global_load_dword v43, v[70:71], off nt
	s_nop 0
	global_load_dword v41, v[72:73], off nt
	global_load_dword v36, v[74:75], off nt
	global_load_dword v38, v[76:77], off nt
	global_load_dword v37, v[78:79], off nt
	global_load_dword v0, v[80:81], off nt
	s_andn2_b64 vcc, exec, s[28:29]
	v_add_lshl_u32 v40, s26, v12, 2
	s_cbranch_vccnz .LBB0_240
	v_lshlrev_b32_e32 v64, 2, v64
	global_load_dword v69, v64, s[46:47]
	global_load_dword v70, v40, s[46:47] offset:8
	global_load_dword v71, v40, s[46:47] offset:16
	s_nop 0
	global_load_dword v64, v40, s[46:47] offset:24
	v_add_u32_e32 v72, v14, v16
	s_waitcnt vmcnt(3)
	v_mul_f32_e32 v73, v68, v69
	s_waitcnt vmcnt(2)
	v_mul_f32_e32 v70, v67, v70
	s_waitcnt vmcnt(1)
	v_mul_f32_e32 v69, v66, v71
	ds_write_b32 v15, v73
	ds_write_b32 v72, v70
	s_cbranch_execnz .LBB0_68

.LBB0_91:
	s_and_b64 vcc, exec, s[2:3]
	s_cbranch_vccz .LBB0_144
	v_cndmask_b32_e64 v0, 0, 1, s[30:31]
	s_mov_b64 s[70:71], -1
	s_cmp_gt_i32 s72, 4
	v_cmp_ne_u32_e64 s[2:3], 1, v0
	s_cbranch_scc0 .LBB0_118
	s_lshl_b32 s26, s67, 6
	v_or_b32_e32 v64, s26, v12
	v_lshlrev_b32_e32 v0, 11, v64
	v_or3_b32 v0, v0, v13, s66
	v_lshlrev_b32_e32 v0, 2, v0
	v_lshl_add_u64 v[36:37], s[44:45], 0, v[0:1]
	v_add_co_u32_e32 v38, vcc, 0x1000, v36
	s_nop 1
	v_addc_co_u32_e32 v39, vcc, 0, v37, vcc
	v_add_co_u32_e32 v40, vcc, 0x5000, v36
	s_nop 1
	v_addc_co_u32_e32 v41, vcc, 0, v37, vcc
	v_add_co_u32_e32 v42, vcc, 0x9000, v36
	s_nop 1
	v_addc_co_u32_e32 v43, vcc, 0, v37, vcc
	v_add_co_u32_e32 v44, vcc, 0xd000, v36
	s_nop 1
	v_addc_co_u32_e32 v45, vcc, 0, v37, vcc
	v_add_co_u32_e32 v46, vcc, 0x11000, v36
	s_nop 1
	v_addc_co_u32_e32 v47, vcc, 0, v37, vcc
	v_add_co_u32_e32 v48, vcc, 0x15000, v36
	s_nop 1
	v_addc_co_u32_e32 v49, vcc, 0, v37, vcc
	v_add_co_u32_e32 v50, vcc, 0x19000, v36
	s_nop 1
	v_addc_co_u32_e32 v51, vcc, 0, v37, vcc
	v_add_co_u32_e32 v52, vcc, 0x1d000, v36
	s_nop 1
	v_addc_co_u32_e32 v53, vcc, 0, v37, vcc
	global_load_dword v68, v[38:39], off nt
	global_load_dword v67, v[40:41], off nt
	global_load_dword v66, v[42:43], off nt
	global_load_dword v65, v[44:45], off nt
	global_load_dword v58, v[46:47], off nt
	global_load_dword v62, v[48:49], off nt
	global_load_dword v59, v[50:51], off nt
	global_load_dword v57, v[52:53], off nt
	v_add_co_u32_e32 v38, vcc, 0x21000, v36
	s_nop 1
	v_addc_co_u32_e32 v39, vcc, 0, v37, vcc
	v_add_co_u32_e32 v40, vcc, 0x25000, v36
	s_nop 1
	v_addc_co_u32_e32 v41, vcc, 0, v37, vcc
	v_add_co_u32_e32 v42, vcc, 0x29000, v36
	s_nop 1
	v_addc_co_u32_e32 v43, vcc, 0, v37, vcc
	v_add_co_u32_e32 v44, vcc, 0x2d000, v36
	s_nop 1
	v_addc_co_u32_e32 v45, vcc, 0, v37, vcc
	v_add_co_u32_e32 v46, vcc, 0x31000, v36
	s_nop 1
	v_addc_co_u32_e32 v47, vcc, 0, v37, vcc
	v_add_co_u32_e32 v48, vcc, 0x35000, v36
	s_nop 1
	v_addc_co_u32_e32 v49, vcc, 0, v37, vcc
	v_add_co_u32_e32 v52, vcc, 0x39000, v36
	s_nop 1
	v_addc_co_u32_e32 v53, vcc, 0, v37, vcc
	v_add_co_u32_e32 v70, vcc, 0x3d000, v36
	s_nop 1
	v_addc_co_u32_e32 v71, vcc, 0, v37, vcc
	global_load_dword v60, v[38:39], off nt
	global_load_dword v63, v[40:41], off nt
	global_load_dword v61, v[42:43], off nt
	global_load_dword v56, v[44:45], off nt
	global_load_dword v50, v[46:47], off nt
	global_load_dword v54, v[48:49], off nt
	global_load_dword v51, v[52:53], off nt
	s_nop 0
	global_load_dword v49, v[70:71], off nt
	v_add_co_u32_e32 v38, vcc, 0x41000, v36
	s_nop 1
	v_addc_co_u32_e32 v39, vcc, 0, v37, vcc
	v_add_co_u32_e32 v40, vcc, 0x45000, v36
	s_nop 1
	v_addc_co_u32_e32 v41, vcc, 0, v37, vcc
	v_add_co_u32_e32 v42, vcc, 0x49000, v36
	s_nop 1
	v_addc_co_u32_e32 v43, vcc, 0, v37, vcc
	v_add_co_u32_e32 v44, vcc, 0x4d000, v36
	s_nop 1
	v_addc_co_u32_e32 v45, vcc, 0, v37, vcc
	v_add_co_u32_e32 v46, vcc, 0x51000, v36
	s_nop 1
	v_addc_co_u32_e32 v47, vcc, 0, v37, vcc
	v_add_co_u32_e32 v70, vcc, 0x55000, v36
	s_nop 1
	v_addc_co_u32_e32 v71, vcc, 0, v37, vcc
	v_add_co_u32_e32 v72, vcc, 0x59000, v36
	s_nop 1
	v_addc_co_u32_e32 v73, vcc, 0, v37, vcc
	v_add_co_u32_e32 v74, vcc, 0x5d000, v36
	s_nop 1
	v_addc_co_u32_e32 v75, vcc, 0, v37, vcc
	global_load_dword v52, v[38:39], off nt
	global_load_dword v55, v[40:41], off nt
	global_load_dword v53, v[42:43], off nt
	global_load_dword v48, v[44:45], off nt
	s_nop 0
	global_load_dword v42, v[46:47], off nt
	s_nop 0
	global_load_dword v46, v[70:71], off nt
	global_load_dword v43, v[72:73], off nt
	global_load_dword v41, v[74:75], off nt
	v_add_co_u32_e32 v38, vcc, 0x61000, v36
	s_nop 1
	v_addc_co_u32_e32 v39, vcc, 0, v37, vcc
	v_add_co_u32_e32 v70, vcc, 0x65000, v36
	s_nop 1
	v_addc_co_u32_e32 v71, vcc, 0, v37, vcc
	v_add_co_u32_e32 v72, vcc, 0x69000, v36
	s_nop 1
	v_addc_co_u32_e32 v73, vcc, 0, v37, vcc
	v_add_co_u32_e32 v74, vcc, 0x6d000, v36
	s_nop 1
	v_addc_co_u32_e32 v75, vcc, 0, v37, vcc
	v_add_co_u32_e32 v76, vcc, 0x71000, v36
	s_nop 1
	v_addc_co_u32_e32 v77, vcc, 0, v37, vcc
	v_add_co_u32_e32 v78, vcc, 0x75000, v36
	s_nop 1
	v_addc_co_u32_e32 v79, vcc, 0, v37, vcc
	v_add_co_u32_e32 v80, vcc, 0x79000, v36
	s_nop 1
	v_addc_co_u32_e32 v81, vcc, 0, v37, vcc
	v_add_co_u32_e32 v82, vcc, 0x7d000, v36
	s_nop 1
	v_addc_co_u32_e32 v83, vcc, 0, v37, vcc
	global_load_dword v44, v[38:39], off nt
	global_load_dword v47, v[70:71], off nt
	global_load_dword v45, v[72:73], off nt
	global_load_dword v40, v[74:75], off nt
	global_load_dword v36, v[76:77], off nt
	s_nop 0
	global_load_dword v38, v[78:79], off nt
	global_load_dword v37, v[80:81], off nt
	global_load_dword v0, v[82:83], off nt
	s_and_b64 vcc, exec, s[2:3]
	v_add_lshl_u32 v39, s26, v12, 2
	s_cbranch_vccnz .LBB0_248
	v_lshlrev_b32_e32 v64, 2, v64
	global_load_dword v69, v64, s[42:43]
	global_load_dword v70, v39, s[42:43] offset:8
	global_load_dword v71, v39, s[42:43] offset:16
	s_nop 0
	global_load_dword v64, v39, s[42:43] offset:24
	v_add_u32_e32 v72, v14, v16
	s_waitcnt vmcnt(3)
	v_mul_f32_e32 v73, v68, v69
	s_waitcnt vmcnt(2)
	v_mul_f32_e32 v70, v67, v70
	s_waitcnt vmcnt(1)
	v_mul_f32_e32 v69, v66, v71
	ds_write_b32 v15, v73
	ds_write_b32 v72, v70
	s_cbranch_execnz .LBB0_96

.LBB0_118:
	s_and_b64 vcc, exec, s[70:71]
	s_cbranch_vccz .LBB0_144
	s_lshl_b32 s26, s67, 6
	v_or_b32_e32 v64, s26, v12
	v_lshlrev_b32_e32 v0, 11, v64
	v_or3_b32 v0, v0, v13, s66
	v_lshlrev_b32_e32 v0, 2, v0
	v_lshl_add_u64 v[36:37], s[44:45], 0, v[0:1]
	v_add_co_u32_e32 v38, vcc, 0x4000, v36
	s_nop 1
	v_addc_co_u32_e32 v39, vcc, 0, v37, vcc
	v_add_co_u32_e32 v40, vcc, 0x8000, v36
	s_nop 1
	v_addc_co_u32_e32 v41, vcc, 0, v37, vcc
	v_add_co_u32_e32 v42, vcc, 0xc000, v36
	s_nop 1
	v_addc_co_u32_e32 v43, vcc, 0, v37, vcc
	v_add_co_u32_e32 v44, vcc, 0x10000, v36
	s_nop 1
	v_addc_co_u32_e32 v45, vcc, 0, v37, vcc
	v_add_co_u32_e32 v46, vcc, 0x14000, v36
	s_nop 1
	v_addc_co_u32_e32 v47, vcc, 0, v37, vcc
	v_add_co_u32_e32 v48, vcc, 0x18000, v36
	s_nop 1
	v_addc_co_u32_e32 v49, vcc, 0, v37, vcc
	v_add_co_u32_e32 v50, vcc, 0x1c000, v36
	s_nop 1
	v_addc_co_u32_e32 v51, vcc, 0, v37, vcc
	v_add_co_u32_e32 v52, vcc, 0x20000, v36
	s_nop 1
	v_addc_co_u32_e32 v53, vcc, 0, v37, vcc
	global_load_dword v67, v[38:39], off nt
	global_load_dword v66, v[40:41], off nt
	global_load_dword v65, v[42:43], off nt
	global_load_dword v59, v[44:45], off nt
	global_load_dword v62, v[46:47], off nt
	global_load_dword v60, v[48:49], off nt
	global_load_dword v57, v[50:51], off nt
	global_load_dword v56, v[52:53], off nt
	v_add_co_u32_e32 v38, vcc, 0x24000, v36
	s_nop 1
	v_addc_co_u32_e32 v39, vcc, 0, v37, vcc
	v_add_co_u32_e32 v40, vcc, 0x28000, v36
	s_nop 1
	v_addc_co_u32_e32 v41, vcc, 0, v37, vcc
	v_add_co_u32_e32 v42, vcc, 0x2c000, v36
	s_nop 1
	v_addc_co_u32_e32 v43, vcc, 0, v37, vcc
	v_add_co_u32_e32 v44, vcc, 0x30000, v36
	s_nop 1
	v_addc_co_u32_e32 v45, vcc, 0, v37, vcc
	v_add_co_u32_e32 v46, vcc, 0x34000, v36
	s_nop 1
	v_addc_co_u32_e32 v47, vcc, 0, v37, vcc
	v_add_co_u32_e32 v48, vcc, 0x38000, v36
	s_nop 1
	v_addc_co_u32_e32 v49, vcc, 0, v37, vcc
	v_add_co_u32_e32 v68, vcc, 0x3c000, v36
	s_nop 1
	v_addc_co_u32_e32 v69, vcc, 0, v37, vcc
	v_add_co_u32_e32 v70, vcc, 0x40000, v36
	s_nop 1
	v_addc_co_u32_e32 v71, vcc, 0, v37, vcc
	global_load_dword v63, v[38:39], off nt
	global_load_dword v61, v[40:41], off nt
	global_load_dword v58, v[42:43], off nt
	global_load_dword v51, v[44:45], off nt
	global_load_dword v54, v[46:47], off nt
	global_load_dword v52, v[48:49], off nt
	s_nop 0
	global_load_dword v49, v[68:69], off nt
	global_load_dword v48, v[70:71], off nt
	v_add_co_u32_e32 v38, vcc, 0x44000, v36
	s_nop 1
	v_addc_co_u32_e32 v39, vcc, 0, v37, vcc
	v_add_co_u32_e32 v40, vcc, 0x48000, v36
	s_nop 1
	v_addc_co_u32_e32 v41, vcc, 0, v37, vcc
	v_add_co_u32_e32 v42, vcc, 0x4c000, v36
	s_nop 1
	v_addc_co_u32_e32 v43, vcc, 0, v37, vcc
	v_add_co_u32_e32 v44, vcc, 0x50000, v36
	s_nop 1
	v_addc_co_u32_e32 v45, vcc, 0, v37, vcc
	v_add_co_u32_e32 v46, vcc, 0x54000, v36
	s_nop 1
	v_addc_co_u32_e32 v47, vcc, 0, v37, vcc
	v_add_co_u32_e32 v68, vcc, 0x58000, v36
	s_nop 1
	v_addc_co_u32_e32 v69, vcc, 0, v37, vcc
	v_add_co_u32_e32 v70, vcc, 0x5c000, v36
	s_nop 1
	v_addc_co_u32_e32 v71, vcc, 0, v37, vcc
	v_add_co_u32_e32 v72, vcc, 0x60000, v36
	s_nop 1
	v_addc_co_u32_e32 v73, vcc, 0, v37, vcc
	global_load_dword v55, v[38:39], off nt
	global_load_dword v53, v[40:41], off nt
	global_load_dword v50, v[42:43], off nt
	s_nop 0
	global_load_dword v45, v[44:45], off nt
	s_nop 0
	global_load_dword v47, v[46:47], off nt
	s_nop 0
	global_load_dword v46, v[68:69], off nt
	global_load_dword v42, v[70:71], off nt
	global_load_dword v39, v[72:73], off nt
	v_add_co_u32_e32 v40, vcc, 0x64000, v36
	s_nop 1
	v_addc_co_u32_e32 v41, vcc, 0, v37, vcc
	v_add_co_u32_e32 v70, vcc, 0x68000, v36
	s_nop 1
	v_addc_co_u32_e32 v71, vcc, 0, v37, vcc
	v_add_co_u32_e32 v72, vcc, 0x6c000, v36
	s_nop 1
	v_addc_co_u32_e32 v73, vcc, 0, v37, vcc
	v_add_co_u32_e32 v74, vcc, 0x70000, v36
	s_nop 1
	v_addc_co_u32_e32 v75, vcc, 0, v37, vcc
	v_add_co_u32_e32 v76, vcc, 0x74000, v36
	s_nop 1
	v_addc_co_u32_e32 v77, vcc, 0, v37, vcc
	v_add_co_u32_e32 v78, vcc, 0x78000, v36
	s_nop 1
	v_addc_co_u32_e32 v79, vcc, 0, v37, vcc
	v_add_co_u32_e32 v80, vcc, 0x7c000, v36
	s_nop 1
	v_addc_co_u32_e32 v81, vcc, 0, v37, vcc
	global_load_dword v68, v0, s[44:45]
	global_load_dword v44, v[40:41], off nt
	global_load_dword v43, v[70:71], off nt
	s_nop 0
	global_load_dword v41, v[72:73], off nt
	global_load_dword v36, v[74:75], off nt
	global_load_dword v38, v[76:77], off nt
	global_load_dword v37, v[78:79], off nt
	global_load_dword v0, v[80:81], off nt
	s_and_b64 vcc, exec, s[2:3]
	v_add_lshl_u32 v40, s26, v12, 2
	s_cbranch_vccnz .LBB0_256
	v_lshlrev_b32_e32 v64, 2, v64
	global_load_dword v69, v64, s[42:43]
	global_load_dword v70, v40, s[42:43] offset:8
	global_load_dword v71, v40, s[42:43] offset:16
	s_nop 0
	global_load_dword v64, v40, s[42:43] offset:24
	v_add_u32_e32 v72, v14, v16
	s_waitcnt vmcnt(3)
	v_mul_f32_e32 v73, v68, v69
	s_waitcnt vmcnt(2)
	v_mul_f32_e32 v70, v67, v70
	s_waitcnt vmcnt(1)
	v_mul_f32_e32 v69, v66, v71
	ds_write_b32 v15, v73
	ds_write_b32 v72, v70
	s_cbranch_execnz .LBB0_122

.LBB0_145:
	s_and_b64 vcc, exec, s[2:3]
	s_cbranch_vccz .LBB0_205
	s_cmp_gt_i32 s72, 1
	s_mov_b64 s[2:3], -1
	s_cbranch_scc0 .LBB0_176
	s_cmp_gt_i32 s72, 2
	s_cbranch_scc0 .LBB0_149
	v_lshlrev_b32_e32 v0, 10, v12
	v_lshl_or_b32 v0, s67, 16, v0
	v_or3_b32 v0, v0, v13, s66
	v_lshlrev_b32_e32 v0, 2, v0
	v_lshl_add_u64 v[36:37], s[22:23], 0, v[0:1]
	v_add_co_u32_e32 v38, vcc, 0x2000, v36
	global_load_dword v0, v0, s[22:23]
	s_nop 0
	v_addc_co_u32_e32 v39, vcc, 0, v37, vcc
	v_add_co_u32_e32 v40, vcc, 0x4000, v36
	s_lshl_b32 s26, s67, 7
	s_nop 0
	v_addc_co_u32_e32 v41, vcc, 0, v37, vcc
	v_add_co_u32_e32 v42, vcc, 0x6000, v36
	s_mov_b64 s[2:3], 0
	s_nop 0
	v_addc_co_u32_e32 v43, vcc, 0, v37, vcc
	v_add_co_u32_e32 v44, vcc, 0x8000, v36
	s_nop 1
	v_addc_co_u32_e32 v45, vcc, 0, v37, vcc
	v_add_co_u32_e32 v46, vcc, 0xa000, v36
	s_nop 1
	v_addc_co_u32_e32 v47, vcc, 0, v37, vcc
	v_add_co_u32_e32 v48, vcc, 0xc000, v36
	s_nop 1
	v_addc_co_u32_e32 v49, vcc, 0, v37, vcc
	v_add_co_u32_e32 v50, vcc, 0xe000, v36
	s_nop 1
	v_addc_co_u32_e32 v51, vcc, 0, v37, vcc
	v_add_co_u32_e32 v52, vcc, 0x10000, v36
	s_nop 1
	v_addc_co_u32_e32 v53, vcc, 0, v37, vcc
	global_load_dword v54, v[38:39], off nt
	global_load_dword v55, v[40:41], off nt
	global_load_dword v56, v[42:43], off nt
	global_load_dword v57, v[44:45], off nt
	global_load_dword v58, v[46:47], off nt
	global_load_dword v59, v[48:49], off nt
	global_load_dword v60, v[50:51], off nt
	global_load_dword v61, v[52:53], off nt
	v_add_co_u32_e32 v38, vcc, 0x12000, v36
	s_nop 1
	v_addc_co_u32_e32 v39, vcc, 0, v37, vcc
	v_add_co_u32_e32 v40, vcc, 0x14000, v36
	s_nop 1
	v_addc_co_u32_e32 v41, vcc, 0, v37, vcc
	v_add_co_u32_e32 v42, vcc, 0x16000, v36
	s_nop 1
	v_addc_co_u32_e32 v43, vcc, 0, v37, vcc
	v_add_co_u32_e32 v44, vcc, 0x18000, v36
	s_nop 1
	v_addc_co_u32_e32 v45, vcc, 0, v37, vcc
	v_add_co_u32_e32 v46, vcc, 0x1a000, v36
	s_nop 1
	v_addc_co_u32_e32 v47, vcc, 0, v37, vcc
	v_add_co_u32_e32 v48, vcc, 0x1c000, v36
	s_nop 1
	v_addc_co_u32_e32 v49, vcc, 0, v37, vcc
	v_add_co_u32_e32 v50, vcc, 0x1e000, v36
	s_nop 1
	v_addc_co_u32_e32 v51, vcc, 0, v37, vcc
	v_add_co_u32_e32 v52, vcc, 0x20000, v36
	s_nop 1
	v_addc_co_u32_e32 v53, vcc, 0, v37, vcc
	global_load_dword v62, v[38:39], off nt
	global_load_dword v63, v[40:41], off nt
	global_load_dword v64, v[42:43], off nt
	global_load_dword v65, v[44:45], off nt
	global_load_dword v66, v[46:47], off nt
	global_load_dword v67, v[48:49], off nt
	global_load_dword v68, v[50:51], off nt
	global_load_dword v69, v[52:53], off nt
	v_add_co_u32_e32 v38, vcc, 0x22000, v36
	s_nop 1
	v_addc_co_u32_e32 v39, vcc, 0, v37, vcc
	v_add_co_u32_e32 v40, vcc, 0x24000, v36
	s_nop 1
	v_addc_co_u32_e32 v41, vcc, 0, v37, vcc
	v_add_co_u32_e32 v42, vcc, 0x26000, v36
	s_nop 1
	v_addc_co_u32_e32 v43, vcc, 0, v37, vcc
	v_add_co_u32_e32 v44, vcc, 0x28000, v36
	s_nop 1
	v_addc_co_u32_e32 v45, vcc, 0, v37, vcc
	v_add_co_u32_e32 v46, vcc, 0x2a000, v36
	s_nop 1
	v_addc_co_u32_e32 v47, vcc, 0, v37, vcc
	v_add_co_u32_e32 v48, vcc, 0x2c000, v36
	s_nop 1
	v_addc_co_u32_e32 v49, vcc, 0, v37, vcc
	v_add_co_u32_e32 v50, vcc, 0x2e000, v36
	s_nop 1
	v_addc_co_u32_e32 v51, vcc, 0, v37, vcc
	v_add_co_u32_e32 v52, vcc, 0x30000, v36
	s_nop 1
	v_addc_co_u32_e32 v53, vcc, 0, v37, vcc
	global_load_dword v70, v[38:39], off nt
	global_load_dword v71, v[40:41], off nt
	global_load_dword v72, v[42:43], off nt
	global_load_dword v73, v[44:45], off nt
	global_load_dword v74, v[46:47], off nt
	global_load_dword v75, v[48:49], off nt
	s_nop 0
	global_load_dword v50, v[50:51], off nt
	s_nop 0
	global_load_dword v51, v[52:53], off nt
	v_add_co_u32_e32 v38, vcc, 0x32000, v36
	s_nop 1
	v_addc_co_u32_e32 v39, vcc, 0, v37, vcc
	v_add_co_u32_e32 v40, vcc, 0x34000, v36
	s_nop 1
	v_addc_co_u32_e32 v41, vcc, 0, v37, vcc
	v_add_co_u32_e32 v42, vcc, 0x36000, v36
	s_nop 1
	v_addc_co_u32_e32 v43, vcc, 0, v37, vcc
	v_add_co_u32_e32 v44, vcc, 0x38000, v36
	s_nop 1
	v_addc_co_u32_e32 v45, vcc, 0, v37, vcc
	v_add_co_u32_e32 v46, vcc, 0x3a000, v36
	s_nop 1
	v_addc_co_u32_e32 v47, vcc, 0, v37, vcc
	v_add_co_u32_e32 v48, vcc, 0x3c000, v36
	s_nop 1
	v_addc_co_u32_e32 v49, vcc, 0, v37, vcc
	v_add_co_u32_e32 v36, vcc, 0x3e000, v36
	s_nop 1
	v_addc_co_u32_e32 v37, vcc, 0, v37, vcc
	global_load_dword v38, v[38:39], off nt
	s_nop 0
	global_load_dword v39, v[40:41], off nt
	s_nop 0
	global_load_dword v40, v[42:43], off nt
	global_load_dword v41, v[44:45], off nt
	s_nop 0
	global_load_dword v42, v[46:47], off nt
	global_load_dword v43, v[48:49], off nt
	s_nop 0
	global_load_dword v36, v[36:37], off nt
	s_waitcnt vmcnt(30)
	ds_write2_b32 v15, v0, v54 offset1:66
	s_waitcnt vmcnt(28)
	ds_write2_b32 v15, v55, v56 offset0:132 offset1:198
	v_add_u32_e32 v0, 0x400, v15
	s_waitcnt vmcnt(26)
	ds_write2_b32 v0, v57, v58 offset0:8 offset1:74
	s_waitcnt vmcnt(24)
	ds_write2_b32 v0, v59, v60 offset0:140 offset1:206
	v_add_u32_e32 v0, 0x800, v15
	s_waitcnt vmcnt(22)
	ds_write2_b32 v0, v61, v62 offset0:16 offset1:82
	s_waitcnt vmcnt(20)
	ds_write2_b32 v0, v63, v64 offset0:148 offset1:214
	v_add_u32_e32 v0, 0xc00, v15
	s_waitcnt vmcnt(18)
	ds_write2_b32 v0, v65, v66 offset0:24 offset1:90
	s_waitcnt vmcnt(16)
	ds_write2_b32 v0, v67, v68 offset0:156 offset1:222
	v_add_u32_e32 v0, 0x1000, v15
	s_waitcnt vmcnt(14)
	ds_write2_b32 v0, v69, v70 offset0:32 offset1:98
	s_waitcnt vmcnt(12)
	ds_write2_b32 v0, v71, v72 offset0:164 offset1:230
	v_add_u32_e32 v0, 0x1400, v15
	s_waitcnt vmcnt(10)
	ds_write2_b32 v0, v73, v74 offset0:40 offset1:106
	s_waitcnt vmcnt(8)
	ds_write2_b32 v0, v75, v50 offset0:172 offset1:238
	v_add_u32_e32 v0, 0x1800, v15
	s_waitcnt vmcnt(6)
	ds_write2_b32 v0, v51, v38 offset0:48 offset1:114
	s_waitcnt vmcnt(4)
	ds_write2_b32 v0, v39, v40 offset0:180 offset1:246
	v_add_u32_e32 v0, 0x1c00, v15
	s_waitcnt vmcnt(2)
	ds_write2_b32 v0, v41, v42 offset0:56 offset1:122
	s_waitcnt vmcnt(0)
	ds_write2_b32 v0, v43, v36 offset0:188 offset1:254
	s_waitcnt lgkmcnt(0)
	ds_read2_b32 v[40:41], v31 offset0:33 offset1:41
	ds_read2_b32 v[42:43], v31 offset1:8
	ds_read2_b32 v[44:45], v31 offset0:66 offset1:74
	ds_read2_b32 v[46:47], v31 offset0:99 offset1:107
	ds_read2_b32 v[48:49], v31 offset0:132 offset1:140
	ds_read2_b32 v[50:51], v31 offset0:165 offset1:173
	ds_read2_b32 v[52:53], v31 offset0:198 offset1:206
	ds_read2_b32 v[54:55], v31 offset0:231 offset1:239
	v_or_b32_e32 v0, s66, v30
	v_lshl_add_u64 v[56:57], v[8:9], 0, s[26:27]
	v_lshlrev_b32_e32 v0, 11, v0
	s_waitcnt lgkmcnt(6)
	v_cvt_pk_bf16_f32 v36, v42, v40
	s_waitcnt lgkmcnt(4)
	v_cvt_pk_bf16_f32 v37, v44, v46
	s_waitcnt lgkmcnt(2)
	v_cvt_pk_bf16_f32 v38, v48, v50
	s_waitcnt lgkmcnt(0)
	v_cvt_pk_bf16_f32 v39, v52, v54
	v_lshl_add_u64 v[58:59], v[56:57], 0, v[0:1]
	global_store_dwordx4 v[58:59], v[36:39], off
	v_or_b32_e32 v0, s66, v32
	v_lshlrev_b32_e32 v0, 11, v0
	v_cvt_pk_bf16_f32 v36, v43, v41
	v_cvt_pk_bf16_f32 v37, v45, v47
	v_cvt_pk_bf16_f32 v38, v49, v51
	v_cvt_pk_bf16_f32 v39, v53, v55
	ds_read2_b32 v[42:43], v31 offset0:49 offset1:57
	ds_read2_b32 v[44:45], v31 offset0:16 offset1:24
	ds_read2_b32 v[46:47], v31 offset0:82 offset1:90
	ds_read2_b32 v[48:49], v31 offset0:115 offset1:123
	ds_read2_b32 v[50:51], v31 offset0:148 offset1:156
	ds_read2_b32 v[52:53], v31 offset0:181 offset1:189
	ds_read2_b32 v[54:55], v31 offset0:214 offset1:222
	ds_read2_b32 v[58:59], v31 offset0:247 offset1:255
	v_lshl_add_u64 v[40:41], v[56:57], 0, v[0:1]
	v_or_b32_e32 v0, s66, v33
	v_lshlrev_b32_e32 v0, 11, v0
	global_store_dwordx4 v[40:41], v[36:39], off
	v_lshl_add_u64 v[40:41], v[56:57], 0, v[0:1]
	v_or_b32_e32 v0, s66, v34
	s_waitcnt lgkmcnt(6)
	v_cvt_pk_bf16_f32 v36, v44, v42
	s_waitcnt lgkmcnt(4)
	v_cvt_pk_bf16_f32 v37, v46, v48
	s_waitcnt lgkmcnt(2)
	v_cvt_pk_bf16_f32 v38, v50, v52
	s_waitcnt lgkmcnt(0)
	v_cvt_pk_bf16_f32 v39, v54, v58
	v_lshlrev_b32_e32 v0, 11, v0
	global_store_dwordx4 v[40:41], v[36:39], off
	v_lshl_add_u64 v[40:41], v[56:57], 0, v[0:1]
	s_nop 0
	v_cvt_pk_bf16_f32 v36, v45, v43
	v_cvt_pk_bf16_f32 v37, v47, v49
	v_cvt_pk_bf16_f32 v38, v51, v53
	v_cvt_pk_bf16_f32 v39, v55, v59
	global_store_dwordx4 v[40:41], v[36:39], off
	s_waitcnt lgkmcnt(0)
.LBB0_149:
	s_andn2_b64 vcc, exec, s[2:3]
	s_cbranch_vccnz .LBB0_175
	s_lshl_b32 s26, s67, 6
	s_or_b32 s70, s66, 0x800
	v_or_b32_e32 v64, s26, v12
	v_or_b32_e32 v0, s70, v13
	v_mul_u32_u24_e32 v36, 0xc00, v64
	v_add_lshl_u32 v0, v36, v0, 2
	v_lshl_add_u64 v[36:37], s[12:13], 0, v[0:1]
	v_add_co_u32_e32 v38, vcc, 0x6000, v36
	s_nop 1
	v_addc_co_u32_e32 v39, vcc, 0, v37, vcc
	v_add_co_u32_e32 v40, vcc, 0xc000, v36
	s_nop 1
	v_addc_co_u32_e32 v41, vcc, 0, v37, vcc
	v_add_co_u32_e32 v42, vcc, 0x12000, v36
	s_nop 1
	v_addc_co_u32_e32 v43, vcc, 0, v37, vcc
	v_add_co_u32_e32 v44, vcc, 0x18000, v36
	s_nop 1
	v_addc_co_u32_e32 v45, vcc, 0, v37, vcc
	v_add_co_u32_e32 v46, vcc, 0x1e000, v36
	s_nop 1
	v_addc_co_u32_e32 v47, vcc, 0, v37, vcc
	v_add_co_u32_e32 v48, vcc, 0x24000, v36
	s_nop 1
	v_addc_co_u32_e32 v49, vcc, 0, v37, vcc
	v_add_co_u32_e32 v50, vcc, 0x2a000, v36
	s_nop 1
	v_addc_co_u32_e32 v51, vcc, 0, v37, vcc
	v_add_co_u32_e32 v52, vcc, 0x30000, v36
	s_nop 1
	v_addc_co_u32_e32 v53, vcc, 0, v37, vcc
	global_load_dword v67, v[38:39], off nt
	global_load_dword v66, v[40:41], off nt
	global_load_dword v65, v[42:43], off nt
	global_load_dword v59, v[44:45], off nt
	global_load_dword v62, v[46:47], off nt
	global_load_dword v60, v[48:49], off nt
	global_load_dword v57, v[50:51], off nt
	global_load_dword v56, v[52:53], off nt
	v_add_co_u32_e32 v38, vcc, 0x36000, v36
	s_nop 1
	v_addc_co_u32_e32 v39, vcc, 0, v37, vcc
	v_add_co_u32_e32 v40, vcc, 0x3c000, v36
	s_nop 1
	v_addc_co_u32_e32 v41, vcc, 0, v37, vcc
	v_add_co_u32_e32 v42, vcc, 0x42000, v36
	s_nop 1
	v_addc_co_u32_e32 v43, vcc, 0, v37, vcc
	v_add_co_u32_e32 v44, vcc, 0x48000, v36
	s_nop 1
	v_addc_co_u32_e32 v45, vcc, 0, v37, vcc
	v_add_co_u32_e32 v46, vcc, 0x4e000, v36
	s_nop 1
	v_addc_co_u32_e32 v47, vcc, 0, v37, vcc
	v_add_co_u32_e32 v48, vcc, 0x54000, v36
	s_nop 1
	v_addc_co_u32_e32 v49, vcc, 0, v37, vcc
	v_add_co_u32_e32 v68, vcc, 0x5a000, v36
	s_nop 1
	v_addc_co_u32_e32 v69, vcc, 0, v37, vcc
	v_add_co_u32_e32 v70, vcc, 0x60000, v36
	s_nop 1
	v_addc_co_u32_e32 v71, vcc, 0, v37, vcc
	global_load_dword v63, v[38:39], off nt
	global_load_dword v61, v[40:41], off nt
	global_load_dword v58, v[42:43], off nt
	global_load_dword v51, v[44:45], off nt
	global_load_dword v54, v[46:47], off nt
	global_load_dword v52, v[48:49], off nt
	s_nop 0
	global_load_dword v49, v[68:69], off nt
	global_load_dword v48, v[70:71], off nt
	v_add_co_u32_e32 v38, vcc, 0x66000, v36
	s_nop 1
	v_addc_co_u32_e32 v39, vcc, 0, v37, vcc
	v_add_co_u32_e32 v40, vcc, 0x6c000, v36
	s_nop 1
	v_addc_co_u32_e32 v41, vcc, 0, v37, vcc
	v_add_co_u32_e32 v42, vcc, 0x72000, v36
	s_nop 1
	v_addc_co_u32_e32 v43, vcc, 0, v37, vcc
	v_add_co_u32_e32 v44, vcc, 0x78000, v36
	s_nop 1
	v_addc_co_u32_e32 v45, vcc, 0, v37, vcc
	v_add_co_u32_e32 v46, vcc, 0x7e000, v36
	s_nop 1
	v_addc_co_u32_e32 v47, vcc, 0, v37, vcc
	v_add_co_u32_e32 v68, vcc, 0x84000, v36
	s_nop 1
	v_addc_co_u32_e32 v69, vcc, 0, v37, vcc
	v_add_co_u32_e32 v70, vcc, 0x8a000, v36
	s_nop 1
	v_addc_co_u32_e32 v71, vcc, 0, v37, vcc
	v_add_co_u32_e32 v72, vcc, 0x90000, v36
	s_nop 1
	v_addc_co_u32_e32 v73, vcc, 0, v37, vcc
	global_load_dword v55, v[38:39], off nt
	global_load_dword v53, v[40:41], off nt
	global_load_dword v50, v[42:43], off nt
	s_nop 0
	global_load_dword v45, v[44:45], off nt
	s_nop 0
	global_load_dword v47, v[46:47], off nt
	s_nop 0
	global_load_dword v46, v[68:69], off nt
	global_load_dword v42, v[70:71], off nt
	global_load_dword v39, v[72:73], off nt
	v_add_co_u32_e32 v40, vcc, 0x96000, v36
	s_nop 1
	v_addc_co_u32_e32 v41, vcc, 0, v37, vcc
	v_add_co_u32_e32 v70, vcc, 0x9c000, v36
	s_nop 1
	v_addc_co_u32_e32 v71, vcc, 0, v37, vcc
	v_add_co_u32_e32 v72, vcc, 0xa2000, v36
	s_nop 1
	v_addc_co_u32_e32 v73, vcc, 0, v37, vcc
	v_add_co_u32_e32 v74, vcc, 0xa8000, v36
	s_nop 1
	v_addc_co_u32_e32 v75, vcc, 0, v37, vcc
	v_add_co_u32_e32 v76, vcc, 0xae000, v36
	s_nop 1
	v_addc_co_u32_e32 v77, vcc, 0, v37, vcc
	v_add_co_u32_e32 v78, vcc, 0xb4000, v36
	s_nop 1
	v_addc_co_u32_e32 v79, vcc, 0, v37, vcc
	v_add_co_u32_e32 v80, vcc, 0xba000, v36
	s_nop 1
	v_addc_co_u32_e32 v81, vcc, 0, v37, vcc
	global_load_dword v68, v0, s[12:13]
	global_load_dword v44, v[40:41], off nt
	global_load_dword v43, v[70:71], off nt
	s_nop 0
	global_load_dword v41, v[72:73], off nt
	global_load_dword v36, v[74:75], off nt
	global_load_dword v38, v[76:77], off nt
	global_load_dword v37, v[78:79], off nt
	global_load_dword v0, v[80:81], off nt
	v_cndmask_b32_e64 v40, 0, 1, s[34:35]
	v_cmp_ne_u32_e64 s[2:3], 1, v40
	s_andn2_b64 vcc, exec, s[34:35]
	v_add_lshl_u32 v40, s26, v12, 2
	s_cbranch_vccnz .LBB0_264
	v_lshlrev_b32_e32 v64, 2, v64
	global_load_dword v69, v64, s[10:11]
	global_load_dword v70, v40, s[10:11] offset:8
	global_load_dword v71, v40, s[10:11] offset:16
	s_nop 0
	global_load_dword v64, v40, s[10:11] offset:24
	v_add_u32_e32 v72, v14, v16
	s_waitcnt vmcnt(3)
	v_mul_f32_e32 v73, v68, v69
	s_waitcnt vmcnt(2)
	v_mul_f32_e32 v70, v67, v70
	s_waitcnt vmcnt(1)
	v_mul_f32_e32 v69, v66, v71
	ds_write_b32 v15, v73
	ds_write_b32 v72, v70
	s_andn2_b64 vcc, exec, s[36:37]
	s_cbranch_vccnz .LBB0_153

.LBB0_207:
	v_lshlrev_b32_e32 v0, 10, v12
	v_lshl_or_b32 v0, s67, 16, v0
	v_or3_b32 v0, v0, v13, s66
	v_lshlrev_b32_e32 v0, 2, v0
	v_lshl_add_u64 v[36:37], s[54:55], 0, v[0:1]
	v_add_co_u32_e32 v38, vcc, 0x2000, v36
	global_load_dword v0, v0, s[54:55]
	s_nop 0
	v_addc_co_u32_e32 v39, vcc, 0, v37, vcc
	v_add_co_u32_e32 v40, vcc, 0x4000, v36
	s_lshl_b32 s26, s67, 7
	s_nop 0
	v_addc_co_u32_e32 v41, vcc, 0, v37, vcc
	v_add_co_u32_e32 v42, vcc, 0x6000, v36
	s_nop 1
	v_addc_co_u32_e32 v43, vcc, 0, v37, vcc
	v_add_co_u32_e32 v44, vcc, 0x8000, v36
	s_nop 1
	v_addc_co_u32_e32 v45, vcc, 0, v37, vcc
	v_add_co_u32_e32 v46, vcc, 0xa000, v36
	s_nop 1
	v_addc_co_u32_e32 v47, vcc, 0, v37, vcc
	v_add_co_u32_e32 v48, vcc, 0xc000, v36
	s_nop 1
	v_addc_co_u32_e32 v49, vcc, 0, v37, vcc
	v_add_co_u32_e32 v50, vcc, 0xe000, v36
	s_nop 1
	v_addc_co_u32_e32 v51, vcc, 0, v37, vcc
	v_add_co_u32_e32 v52, vcc, 0x10000, v36
	s_nop 1
	v_addc_co_u32_e32 v53, vcc, 0, v37, vcc
	global_load_dword v54, v[38:39], off nt
	global_load_dword v55, v[40:41], off nt
	global_load_dword v56, v[42:43], off nt
	global_load_dword v57, v[44:45], off nt
	global_load_dword v58, v[46:47], off nt
	global_load_dword v59, v[48:49], off nt
	global_load_dword v60, v[50:51], off nt
	global_load_dword v61, v[52:53], off nt
	v_add_co_u32_e32 v38, vcc, 0x12000, v36
	s_nop 1
	v_addc_co_u32_e32 v39, vcc, 0, v37, vcc
	v_add_co_u32_e32 v40, vcc, 0x14000, v36
	s_nop 1
	v_addc_co_u32_e32 v41, vcc, 0, v37, vcc
	v_add_co_u32_e32 v42, vcc, 0x16000, v36
	s_nop 1
	v_addc_co_u32_e32 v43, vcc, 0, v37, vcc
	v_add_co_u32_e32 v44, vcc, 0x18000, v36
	s_nop 1
	v_addc_co_u32_e32 v45, vcc, 0, v37, vcc
	v_add_co_u32_e32 v46, vcc, 0x1a000, v36
	s_nop 1
	v_addc_co_u32_e32 v47, vcc, 0, v37, vcc
	v_add_co_u32_e32 v48, vcc, 0x1c000, v36
	s_nop 1
	v_addc_co_u32_e32 v49, vcc, 0, v37, vcc
	v_add_co_u32_e32 v50, vcc, 0x1e000, v36
	s_nop 1
	v_addc_co_u32_e32 v51, vcc, 0, v37, vcc
	v_add_co_u32_e32 v52, vcc, 0x20000, v36
	s_nop 1
	v_addc_co_u32_e32 v53, vcc, 0, v37, vcc
	global_load_dword v62, v[38:39], off nt
	global_load_dword v63, v[40:41], off nt
	global_load_dword v64, v[42:43], off nt
	global_load_dword v65, v[44:45], off nt
	global_load_dword v66, v[46:47], off nt
	global_load_dword v67, v[48:49], off nt
	global_load_dword v68, v[50:51], off nt
	global_load_dword v69, v[52:53], off nt
	v_add_co_u32_e32 v38, vcc, 0x22000, v36
	s_nop 1
	v_addc_co_u32_e32 v39, vcc, 0, v37, vcc
	v_add_co_u32_e32 v40, vcc, 0x24000, v36
	s_nop 1
	v_addc_co_u32_e32 v41, vcc, 0, v37, vcc
	v_add_co_u32_e32 v42, vcc, 0x26000, v36
	s_nop 1
	v_addc_co_u32_e32 v43, vcc, 0, v37, vcc
	v_add_co_u32_e32 v44, vcc, 0x28000, v36
	s_nop 1
	v_addc_co_u32_e32 v45, vcc, 0, v37, vcc
	v_add_co_u32_e32 v46, vcc, 0x2a000, v36
	s_nop 1
	v_addc_co_u32_e32 v47, vcc, 0, v37, vcc
	v_add_co_u32_e32 v48, vcc, 0x2c000, v36
	s_nop 1
	v_addc_co_u32_e32 v49, vcc, 0, v37, vcc
	v_add_co_u32_e32 v50, vcc, 0x2e000, v36
	s_nop 1
	v_addc_co_u32_e32 v51, vcc, 0, v37, vcc
	v_add_co_u32_e32 v52, vcc, 0x30000, v36
	s_nop 1
	v_addc_co_u32_e32 v53, vcc, 0, v37, vcc
	global_load_dword v70, v[38:39], off nt
	global_load_dword v71, v[40:41], off nt
	global_load_dword v72, v[42:43], off nt
	global_load_dword v73, v[44:45], off nt
	global_load_dword v74, v[46:47], off nt
	global_load_dword v75, v[48:49], off nt
	s_nop 0
	global_load_dword v50, v[50:51], off nt
	s_nop 0
	global_load_dword v51, v[52:53], off nt
	v_add_co_u32_e32 v38, vcc, 0x32000, v36
	s_nop 1
	v_addc_co_u32_e32 v39, vcc, 0, v37, vcc
	v_add_co_u32_e32 v40, vcc, 0x34000, v36
	s_nop 1
	v_addc_co_u32_e32 v41, vcc, 0, v37, vcc
	v_add_co_u32_e32 v42, vcc, 0x36000, v36
	s_nop 1
	v_addc_co_u32_e32 v43, vcc, 0, v37, vcc
	v_add_co_u32_e32 v44, vcc, 0x38000, v36
	s_nop 1
	v_addc_co_u32_e32 v45, vcc, 0, v37, vcc
	v_add_co_u32_e32 v46, vcc, 0x3a000, v36
	s_nop 1
	v_addc_co_u32_e32 v47, vcc, 0, v37, vcc
	v_add_co_u32_e32 v48, vcc, 0x3c000, v36
	s_nop 1
	v_addc_co_u32_e32 v49, vcc, 0, v37, vcc
	v_add_co_u32_e32 v36, vcc, 0x3e000, v36
	s_nop 1
	v_addc_co_u32_e32 v37, vcc, 0, v37, vcc
	global_load_dword v38, v[38:39], off nt
	s_nop 0
	global_load_dword v39, v[40:41], off nt
	s_nop 0
	global_load_dword v40, v[42:43], off nt
	global_load_dword v41, v[44:45], off nt
	s_nop 0
	global_load_dword v42, v[46:47], off nt
	global_load_dword v43, v[48:49], off nt
	s_nop 0
	global_load_dword v36, v[36:37], off nt
	s_waitcnt vmcnt(30)
	ds_write2_b32 v15, v0, v54 offset1:66
	s_waitcnt vmcnt(28)
	ds_write2_b32 v15, v55, v56 offset0:132 offset1:198
	v_add_u32_e32 v0, 0x400, v15
	s_waitcnt vmcnt(26)
	ds_write2_b32 v0, v57, v58 offset0:8 offset1:74
	s_waitcnt vmcnt(24)
	ds_write2_b32 v0, v59, v60 offset0:140 offset1:206
	v_add_u32_e32 v0, 0x800, v15
	s_waitcnt vmcnt(22)
	ds_write2_b32 v0, v61, v62 offset0:16 offset1:82
	s_waitcnt vmcnt(20)
	ds_write2_b32 v0, v63, v64 offset0:148 offset1:214
	v_add_u32_e32 v0, 0xc00, v15
	s_waitcnt vmcnt(18)
	ds_write2_b32 v0, v65, v66 offset0:24 offset1:90
	s_waitcnt vmcnt(16)
	ds_write2_b32 v0, v67, v68 offset0:156 offset1:222
	v_add_u32_e32 v0, 0x1000, v15
	s_waitcnt vmcnt(14)
	ds_write2_b32 v0, v69, v70 offset0:32 offset1:98
	s_waitcnt vmcnt(12)
	ds_write2_b32 v0, v71, v72 offset0:164 offset1:230
	v_add_u32_e32 v0, 0x1400, v15
	s_waitcnt vmcnt(10)
	ds_write2_b32 v0, v73, v74 offset0:40 offset1:106
	s_waitcnt vmcnt(8)
	ds_write2_b32 v0, v75, v50 offset0:172 offset1:238
	v_add_u32_e32 v0, 0x1800, v15
	s_waitcnt vmcnt(6)
	ds_write2_b32 v0, v51, v38 offset0:48 offset1:114
	s_waitcnt vmcnt(4)
	ds_write2_b32 v0, v39, v40 offset0:180 offset1:246
	v_add_u32_e32 v0, 0x1c00, v15
	s_waitcnt vmcnt(2)
	ds_write2_b32 v0, v41, v42 offset0:56 offset1:122
	s_waitcnt vmcnt(0)
	ds_write2_b32 v0, v43, v36 offset0:188 offset1:254
	s_waitcnt lgkmcnt(0)
	ds_read2_b32 v[40:41], v31 offset0:33 offset1:41
	ds_read2_b32 v[42:43], v31 offset1:8
	ds_read2_b32 v[44:45], v31 offset0:66 offset1:74
	ds_read2_b32 v[46:47], v31 offset0:99 offset1:107
	ds_read2_b32 v[48:49], v31 offset0:132 offset1:140
	ds_read2_b32 v[50:51], v31 offset0:165 offset1:173
	ds_read2_b32 v[52:53], v31 offset0:198 offset1:206
	ds_read2_b32 v[54:55], v31 offset0:231 offset1:239
	v_or_b32_e32 v0, s66, v30
	v_lshl_add_u64 v[56:57], v[10:11], 0, s[26:27]
	v_lshlrev_b32_e32 v0, 11, v0
	s_waitcnt lgkmcnt(6)
	v_cvt_pk_bf16_f32 v36, v42, v40
	s_waitcnt lgkmcnt(4)
	v_cvt_pk_bf16_f32 v37, v44, v46
	s_waitcnt lgkmcnt(2)
	v_cvt_pk_bf16_f32 v38, v48, v50
	s_waitcnt lgkmcnt(0)
	v_cvt_pk_bf16_f32 v39, v52, v54
	v_lshl_add_u64 v[58:59], v[56:57], 0, v[0:1]
	global_store_dwordx4 v[58:59], v[36:39], off
	v_or_b32_e32 v0, s66, v32
	v_lshlrev_b32_e32 v0, 11, v0
	v_cvt_pk_bf16_f32 v36, v43, v41
	v_cvt_pk_bf16_f32 v37, v45, v47
	v_cvt_pk_bf16_f32 v38, v49, v51
	v_cvt_pk_bf16_f32 v39, v53, v55
	ds_read2_b32 v[42:43], v31 offset0:49 offset1:57
	ds_read2_b32 v[44:45], v31 offset0:16 offset1:24
	ds_read2_b32 v[46:47], v31 offset0:82 offset1:90
	ds_read2_b32 v[48:49], v31 offset0:115 offset1:123
	ds_read2_b32 v[50:51], v31 offset0:148 offset1:156
	ds_read2_b32 v[52:53], v31 offset0:181 offset1:189
	ds_read2_b32 v[54:55], v31 offset0:214 offset1:222
	ds_read2_b32 v[58:59], v31 offset0:247 offset1:255
	v_lshl_add_u64 v[40:41], v[56:57], 0, v[0:1]
	v_or_b32_e32 v0, s66, v33
	v_lshlrev_b32_e32 v0, 11, v0
	global_store_dwordx4 v[40:41], v[36:39], off
	v_lshl_add_u64 v[40:41], v[56:57], 0, v[0:1]
	v_or_b32_e32 v0, s66, v34
	s_waitcnt lgkmcnt(6)
	v_cvt_pk_bf16_f32 v36, v44, v42
	s_waitcnt lgkmcnt(4)
	v_cvt_pk_bf16_f32 v37, v46, v48
	s_waitcnt lgkmcnt(2)
	v_cvt_pk_bf16_f32 v38, v50, v52
	s_waitcnt lgkmcnt(0)
	v_cvt_pk_bf16_f32 v39, v54, v58
	v_lshlrev_b32_e32 v0, 11, v0
	global_store_dwordx4 v[40:41], v[36:39], off
	v_lshl_add_u64 v[40:41], v[56:57], 0, v[0:1]
	s_nop 0
	v_cvt_pk_bf16_f32 v36, v45, v43
	v_cvt_pk_bf16_f32 v37, v47, v49
	v_cvt_pk_bf16_f32 v38, v51, v53
	v_cvt_pk_bf16_f32 v39, v55, v59
	global_store_dwordx4 v[40:41], v[36:39], off
	s_waitcnt lgkmcnt(0)
	s_cbranch_execnz .LBB0_33
